# v11 + wi epilogue: the eight 1/rms LDS reads hoisted to the epilogue head (one LDS wait instead of eight)
# baseline (speedup 1.0000x reference)
.LBB0_149:
	ds_read_b32 v149, v144
	ds_read_b32 v160, v144 offset:64
	ds_read_b32 v161, v144 offset:128
	ds_read_b32 v162, v144 offset:192
	ds_read_b32 v163, v145
	ds_read_b32 v164, v144 offset:576
	ds_read_b32 v165, v144 offset:640
	ds_read_b32 v166, v144 offset:704
	v_pk_mul_f32 v[124:125], v[128:129], v[124:125]
	v_pk_mul_f32 v[126:127], v[130:131], v[126:127]
	v_pk_mul_f32 v[116:117], v[120:121], v[116:117]
	v_pk_mul_f32 v[118:119], v[122:123], v[118:119]
	s_waitcnt lgkmcnt(0)
	v_mul_f32_e32 v152, 0xbfb8aa3b, v149
	v_pk_mul_f32 v[154:155], v[128:129], v[152:153] op_sel_hi:[1,0]
	v_pk_mul_f32 v[128:129], v[130:131], v[152:153] op_sel_hi:[1,0]
	v_exp_f32_e32 v154, v154
	v_exp_f32_e32 v128, v128
	v_exp_f32_e32 v129, v129
	v_exp_f32_e32 v155, v155
	v_mul_f32_e32 v156, v149, v149
	v_pk_mul_f32 v[130:131], v[120:121], v[152:153] op_sel_hi:[1,0]
	v_pk_add_f32 v[128:129], v[128:129], 1.0 op_sel_hi:[1,0]
	v_pk_add_f32 v[154:155], v[154:155], 1.0 op_sel_hi:[1,0]
	v_rcp_f32_e32 v128, v128
	v_rcp_f32_e32 v129, v129
	v_rcp_f32_e32 v154, v154
	v_rcp_f32_e32 v155, v155
	v_exp_f32_e32 v130, v130
	v_exp_f32_e32 v131, v131
	v_pk_mul_f32 v[126:127], v[126:127], v[156:157] op_sel_hi:[1,0]
	v_pk_mul_f32 v[124:125], v[124:125], v[156:157] op_sel_hi:[1,0]
	v_pk_mul_f32 v[126:127], v[126:127], v[128:129]
	v_pk_mul_f32 v[128:129], v[122:123], v[152:153] op_sel_hi:[1,0]
	v_pk_mul_f32 v[124:125], v[124:125], v[154:155]
	v_exp_f32_e32 v128, v128
	v_exp_f32_e32 v129, v129
	v_cvt_pk_bf16_f32 v124, v124, v125
	v_cvt_pk_bf16_f32 v125, v126, v127
	v_pk_add_f32 v[126:127], v[130:131], 1.0 op_sel_hi:[1,0]
	v_pk_add_f32 v[120:121], v[128:129], 1.0 op_sel_hi:[1,0]
	v_rcp_f32_e32 v126, v126
	v_rcp_f32_e32 v127, v127
	v_rcp_f32_e32 v120, v120
	v_rcp_f32_e32 v121, v121
	v_pk_mul_f32 v[116:117], v[116:117], v[156:157] op_sel_hi:[1,0]
	v_pk_mul_f32 v[108:109], v[112:113], v[108:109]
	v_pk_mul_f32 v[116:117], v[116:117], v[126:127]
	v_lshl_or_b32 v150, s54, 7, v146
	v_cvt_pk_bf16_f32 v126, v116, v117
	v_pk_mul_f32 v[116:117], v[118:119], v[156:157] op_sel_hi:[1,0]
	v_lshl_add_u32 v148, s55, 8, v142
	v_pk_mul_f32 v[116:117], v[116:117], v[120:121]
	v_ashrrev_i32_e32 v151, 31, v150
	v_cvt_pk_bf16_f32 v127, v116, v117
	v_mov_b32_e32 v123, v160
	v_mov_b64_e32 v[116:117], s[92:93]
	v_mad_i64_i32 v[120:121], s[34:35], v148, s31, v[116:117]
	v_lshlrev_b64 v[118:119], 1, v[150:151]
	s_waitcnt lgkmcnt(0)
	v_mul_f32_e32 v122, 0xbfb8aa3b, v123
	v_pk_mul_f32 v[128:129], v[112:113], v[122:123] op_sel_hi:[1,0]
	v_pk_mul_f32 v[112:113], v[114:115], v[122:123] op_sel_hi:[1,0]
	v_exp_f32_e32 v128, v128
	v_exp_f32_e32 v112, v112
	v_exp_f32_e32 v113, v113
	v_exp_f32_e32 v129, v129
	v_lshl_add_u64 v[120:121], v[120:121], 0, v[118:119]
	global_store_dwordx4 v[120:121], v[124:127], off
	v_pk_add_f32 v[112:113], v[112:113], 1.0 op_sel_hi:[1,0]
	v_mul_f32_e32 v120, v123, v123
	v_rcp_f32_e32 v112, v112
	v_rcp_f32_e32 v113, v113
	v_pk_add_f32 v[124:125], v[128:129], 1.0 op_sel_hi:[1,0]
	v_pk_mul_f32 v[110:111], v[114:115], v[110:111]
	v_rcp_f32_e32 v124, v124
	v_rcp_f32_e32 v125, v125
	v_pk_mul_f32 v[114:115], v[104:105], v[122:123] op_sel_hi:[1,0]
	v_pk_mul_f32 v[110:111], v[110:111], v[120:121] op_sel_hi:[1,0]
	v_exp_f32_e32 v114, v114
	v_exp_f32_e32 v115, v115
	v_pk_mul_f32 v[110:111], v[110:111], v[112:113]
	v_pk_mul_f32 v[112:113], v[106:107], v[122:123] op_sel_hi:[1,0]
	v_pk_mul_f32 v[108:109], v[108:109], v[120:121] op_sel_hi:[1,0]
	v_exp_f32_e32 v112, v112
	v_exp_f32_e32 v113, v113
	v_pk_mul_f32 v[108:109], v[108:109], v[124:125]
	v_pk_mul_f32 v[100:101], v[104:105], v[100:101]
	v_cvt_pk_bf16_f32 v108, v108, v109
	v_cvt_pk_bf16_f32 v109, v110, v111
	v_pk_add_f32 v[110:111], v[114:115], 1.0 op_sel_hi:[1,0]
	v_pk_add_f32 v[104:105], v[112:113], 1.0 op_sel_hi:[1,0]
	v_rcp_f32_e32 v110, v110
	v_rcp_f32_e32 v111, v111
	v_rcp_f32_e32 v104, v104
	v_rcp_f32_e32 v105, v105
	v_pk_mul_f32 v[100:101], v[100:101], v[120:121] op_sel_hi:[1,0]
	v_pk_mul_f32 v[102:103], v[106:107], v[102:103]
	v_pk_mul_f32 v[100:101], v[100:101], v[110:111]
	v_pk_mul_f32 v[92:93], v[96:97], v[92:93]
	v_cvt_pk_bf16_f32 v110, v100, v101
	v_pk_mul_f32 v[100:101], v[102:103], v[120:121] op_sel_hi:[1,0]
	v_pk_mul_f32 v[94:95], v[98:99], v[94:95]
	v_pk_mul_f32 v[100:101], v[100:101], v[104:105]
	v_pk_mul_f32 v[84:85], v[88:89], v[84:85]
	v_cvt_pk_bf16_f32 v111, v100, v101
	v_mov_b32_e32 v103, v161
	v_or_b32_e32 v100, 16, v148
	v_mad_i64_i32 v[100:101], s[34:35], v100, s31, v[116:117]
	v_lshl_add_u64 v[100:101], v[100:101], 0, v[118:119]
	s_waitcnt lgkmcnt(0)
	v_mul_f32_e32 v102, 0xbfb8aa3b, v103
	v_pk_mul_f32 v[104:105], v[96:97], v[102:103] op_sel_hi:[1,0]
	v_pk_mul_f32 v[96:97], v[98:99], v[102:103] op_sel_hi:[1,0]
	v_exp_f32_e32 v104, v104
	v_exp_f32_e32 v96, v96
	v_exp_f32_e32 v97, v97
	v_exp_f32_e32 v105, v105
	global_store_dwordx4 v[100:101], v[108:111], off
	v_mul_f32_e32 v100, v103, v103
	v_pk_add_f32 v[96:97], v[96:97], 1.0 op_sel_hi:[1,0]
	v_pk_add_f32 v[104:105], v[104:105], 1.0 op_sel_hi:[1,0]
	v_rcp_f32_e32 v96, v96
	v_rcp_f32_e32 v97, v97
	v_rcp_f32_e32 v104, v104
	v_rcp_f32_e32 v105, v105
	v_pk_mul_f32 v[98:99], v[88:89], v[102:103] op_sel_hi:[1,0]
	v_pk_mul_f32 v[94:95], v[94:95], v[100:101] op_sel_hi:[1,0]
	v_exp_f32_e32 v98, v98
	v_exp_f32_e32 v99, v99
	v_pk_mul_f32 v[94:95], v[94:95], v[96:97]
	v_pk_mul_f32 v[96:97], v[90:91], v[102:103] op_sel_hi:[1,0]
	v_pk_mul_f32 v[92:93], v[92:93], v[100:101] op_sel_hi:[1,0]
	v_exp_f32_e32 v96, v96
	v_exp_f32_e32 v97, v97
	v_pk_mul_f32 v[92:93], v[92:93], v[104:105]
	v_pk_mul_f32 v[84:85], v[84:85], v[100:101] op_sel_hi:[1,0]
	v_cvt_pk_bf16_f32 v92, v92, v93
	v_cvt_pk_bf16_f32 v93, v94, v95
	v_pk_add_f32 v[94:95], v[98:99], 1.0 op_sel_hi:[1,0]
	v_pk_add_f32 v[88:89], v[96:97], 1.0 op_sel_hi:[1,0]
	v_rcp_f32_e32 v94, v94
	v_rcp_f32_e32 v95, v95
	v_rcp_f32_e32 v88, v88
	v_rcp_f32_e32 v89, v89
	v_pk_mul_f32 v[86:87], v[90:91], v[86:87]
	v_pk_mul_f32 v[84:85], v[84:85], v[94:95]
	v_pk_mul_f32 v[76:77], v[80:81], v[76:77]
	v_cvt_pk_bf16_f32 v94, v84, v85
	v_pk_mul_f32 v[84:85], v[86:87], v[100:101] op_sel_hi:[1,0]
	v_pk_mul_f32 v[78:79], v[82:83], v[78:79]
	v_pk_mul_f32 v[84:85], v[84:85], v[88:89]
	v_pk_mul_f32 v[68:69], v[72:73], v[68:69]
	v_cvt_pk_bf16_f32 v95, v84, v85
	v_mov_b32_e32 v87, v162
	v_or_b32_e32 v84, 32, v148
	v_mad_i64_i32 v[84:85], s[34:35], v84, s31, v[116:117]
	v_lshl_add_u64 v[84:85], v[84:85], 0, v[118:119]
	s_waitcnt lgkmcnt(0)
	v_mul_f32_e32 v86, 0xbfb8aa3b, v87
	v_pk_mul_f32 v[88:89], v[80:81], v[86:87] op_sel_hi:[1,0]
	v_pk_mul_f32 v[80:81], v[82:83], v[86:87] op_sel_hi:[1,0]
	v_exp_f32_e32 v88, v88
	v_exp_f32_e32 v80, v80
	v_exp_f32_e32 v81, v81
	v_exp_f32_e32 v89, v89
	global_store_dwordx4 v[84:85], v[92:95], off
	v_mul_f32_e32 v84, v87, v87
	v_pk_add_f32 v[80:81], v[80:81], 1.0 op_sel_hi:[1,0]
	v_pk_add_f32 v[88:89], v[88:89], 1.0 op_sel_hi:[1,0]
	v_rcp_f32_e32 v80, v80
	v_rcp_f32_e32 v81, v81
	v_rcp_f32_e32 v88, v88
	v_rcp_f32_e32 v89, v89
	v_pk_mul_f32 v[82:83], v[72:73], v[86:87] op_sel_hi:[1,0]
	v_pk_mul_f32 v[78:79], v[78:79], v[84:85] op_sel_hi:[1,0]
	v_exp_f32_e32 v82, v82
	v_exp_f32_e32 v83, v83
	v_pk_mul_f32 v[78:79], v[78:79], v[80:81]
	v_pk_mul_f32 v[80:81], v[74:75], v[86:87] op_sel_hi:[1,0]
	v_pk_mul_f32 v[76:77], v[76:77], v[84:85] op_sel_hi:[1,0]
	v_exp_f32_e32 v80, v80
	v_exp_f32_e32 v81, v81
	v_pk_mul_f32 v[76:77], v[76:77], v[88:89]
	v_pk_mul_f32 v[68:69], v[68:69], v[84:85] op_sel_hi:[1,0]
	v_cvt_pk_bf16_f32 v76, v76, v77
	v_cvt_pk_bf16_f32 v77, v78, v79
	v_pk_add_f32 v[78:79], v[82:83], 1.0 op_sel_hi:[1,0]
	v_pk_add_f32 v[72:73], v[80:81], 1.0 op_sel_hi:[1,0]
	v_rcp_f32_e32 v78, v78
	v_rcp_f32_e32 v79, v79
	v_rcp_f32_e32 v72, v72
	v_rcp_f32_e32 v73, v73
	v_pk_mul_f32 v[70:71], v[74:75], v[70:71]
	v_pk_mul_f32 v[68:69], v[68:69], v[78:79]
	v_pk_mul_f32 v[60:61], v[64:65], v[60:61]
	v_cvt_pk_bf16_f32 v78, v68, v69
	v_pk_mul_f32 v[68:69], v[70:71], v[84:85] op_sel_hi:[1,0]
	v_pk_mul_f32 v[62:63], v[66:67], v[62:63]
	v_pk_mul_f32 v[68:69], v[68:69], v[72:73]
	v_pk_mul_f32 v[52:53], v[56:57], v[52:53]
	v_cvt_pk_bf16_f32 v79, v68, v69
	v_mov_b32_e32 v71, v163
	v_or_b32_e32 v68, 48, v148
	v_mad_i64_i32 v[68:69], s[34:35], v68, s31, v[116:117]
	v_lshl_add_u64 v[68:69], v[68:69], 0, v[118:119]
	s_waitcnt lgkmcnt(0)
	v_mul_f32_e32 v70, 0xbfb8aa3b, v71
	v_pk_mul_f32 v[72:73], v[64:65], v[70:71] op_sel_hi:[1,0]
	v_pk_mul_f32 v[64:65], v[66:67], v[70:71] op_sel_hi:[1,0]
	v_exp_f32_e32 v72, v72
	v_exp_f32_e32 v64, v64
	v_exp_f32_e32 v65, v65
	v_exp_f32_e32 v73, v73
	global_store_dwordx4 v[68:69], v[76:79], off
	v_mul_f32_e32 v68, v71, v71
	v_pk_add_f32 v[64:65], v[64:65], 1.0 op_sel_hi:[1,0]
	v_pk_add_f32 v[72:73], v[72:73], 1.0 op_sel_hi:[1,0]
	v_rcp_f32_e32 v64, v64
	v_rcp_f32_e32 v65, v65
	v_rcp_f32_e32 v72, v72
	v_rcp_f32_e32 v73, v73
	v_pk_mul_f32 v[66:67], v[56:57], v[70:71] op_sel_hi:[1,0]
	v_pk_mul_f32 v[62:63], v[62:63], v[68:69] op_sel_hi:[1,0]
	v_exp_f32_e32 v66, v66
	v_exp_f32_e32 v67, v67
	v_pk_mul_f32 v[62:63], v[62:63], v[64:65]
	v_pk_mul_f32 v[64:65], v[58:59], v[70:71] op_sel_hi:[1,0]
	v_pk_mul_f32 v[60:61], v[60:61], v[68:69] op_sel_hi:[1,0]
	v_exp_f32_e32 v64, v64
	v_exp_f32_e32 v65, v65
	v_pk_mul_f32 v[60:61], v[60:61], v[72:73]
	v_pk_mul_f32 v[52:53], v[52:53], v[68:69] op_sel_hi:[1,0]
	v_cvt_pk_bf16_f32 v60, v60, v61
	v_cvt_pk_bf16_f32 v61, v62, v63
	v_pk_add_f32 v[62:63], v[66:67], 1.0 op_sel_hi:[1,0]
	v_pk_add_f32 v[56:57], v[64:65], 1.0 op_sel_hi:[1,0]
	v_rcp_f32_e32 v62, v62
	v_rcp_f32_e32 v63, v63
	v_rcp_f32_e32 v56, v56
	v_rcp_f32_e32 v57, v57
	v_pk_mul_f32 v[54:55], v[58:59], v[54:55]
	v_pk_mul_f32 v[52:53], v[52:53], v[62:63]
	v_pk_mul_f32 v[44:45], v[48:49], v[44:45]
	v_cvt_pk_bf16_f32 v62, v52, v53
	v_pk_mul_f32 v[52:53], v[54:55], v[68:69] op_sel_hi:[1,0]
	v_pk_mul_f32 v[46:47], v[50:51], v[46:47]
	v_pk_mul_f32 v[52:53], v[52:53], v[56:57]
	v_pk_mul_f32 v[36:37], v[40:41], v[36:37]
	v_cvt_pk_bf16_f32 v63, v52, v53
	v_mov_b32_e32 v55, v164
	v_add_u32_e32 v52, 0x80, v148
	v_mad_i64_i32 v[52:53], s[34:35], v52, s31, v[116:117]
	v_lshl_add_u64 v[52:53], v[52:53], 0, v[118:119]
	s_waitcnt lgkmcnt(0)
	v_mul_f32_e32 v54, 0xbfb8aa3b, v55
	v_pk_mul_f32 v[56:57], v[48:49], v[54:55] op_sel_hi:[1,0]
	v_pk_mul_f32 v[48:49], v[50:51], v[54:55] op_sel_hi:[1,0]
	v_exp_f32_e32 v56, v56
	v_exp_f32_e32 v48, v48
	v_exp_f32_e32 v49, v49
	v_exp_f32_e32 v57, v57
	global_store_dwordx4 v[52:53], v[60:63], off
	v_mul_f32_e32 v52, v55, v55
	v_pk_add_f32 v[48:49], v[48:49], 1.0 op_sel_hi:[1,0]
	v_pk_add_f32 v[56:57], v[56:57], 1.0 op_sel_hi:[1,0]
	v_rcp_f32_e32 v48, v48
	v_rcp_f32_e32 v49, v49
	v_rcp_f32_e32 v56, v56
	v_rcp_f32_e32 v57, v57
	v_pk_mul_f32 v[50:51], v[40:41], v[54:55] op_sel_hi:[1,0]
	v_pk_mul_f32 v[46:47], v[46:47], v[52:53] op_sel_hi:[1,0]
	v_exp_f32_e32 v50, v50
	v_exp_f32_e32 v51, v51
	v_pk_mul_f32 v[46:47], v[46:47], v[48:49]
	v_pk_mul_f32 v[48:49], v[42:43], v[54:55] op_sel_hi:[1,0]
	v_pk_mul_f32 v[44:45], v[44:45], v[52:53] op_sel_hi:[1,0]
	v_exp_f32_e32 v48, v48
	v_exp_f32_e32 v49, v49
	v_pk_mul_f32 v[44:45], v[44:45], v[56:57]
	v_pk_mul_f32 v[36:37], v[36:37], v[52:53] op_sel_hi:[1,0]
	v_cvt_pk_bf16_f32 v44, v44, v45
	v_cvt_pk_bf16_f32 v45, v46, v47
	v_pk_add_f32 v[46:47], v[50:51], 1.0 op_sel_hi:[1,0]
	v_pk_add_f32 v[40:41], v[48:49], 1.0 op_sel_hi:[1,0]
	v_rcp_f32_e32 v46, v46
	v_rcp_f32_e32 v47, v47
	v_rcp_f32_e32 v40, v40
	v_rcp_f32_e32 v41, v41
	v_pk_mul_f32 v[38:39], v[42:43], v[38:39]
	v_pk_mul_f32 v[36:37], v[36:37], v[46:47]
	v_pk_mul_f32 v[28:29], v[32:33], v[28:29]
	v_cvt_pk_bf16_f32 v46, v36, v37
	v_pk_mul_f32 v[36:37], v[38:39], v[52:53] op_sel_hi:[1,0]
	v_pk_mul_f32 v[30:31], v[34:35], v[30:31]
	v_pk_mul_f32 v[36:37], v[36:37], v[40:41]
	v_pk_mul_f32 v[20:21], v[24:25], v[20:21]
	v_cvt_pk_bf16_f32 v47, v36, v37
	v_mov_b32_e32 v39, v165
	v_add_u32_e32 v36, 0x90, v148
	v_mad_i64_i32 v[36:37], s[34:35], v36, s31, v[116:117]
	v_lshl_add_u64 v[36:37], v[36:37], 0, v[118:119]
	s_waitcnt lgkmcnt(0)
	v_mul_f32_e32 v38, 0xbfb8aa3b, v39
	v_pk_mul_f32 v[40:41], v[32:33], v[38:39] op_sel_hi:[1,0]
	v_pk_mul_f32 v[32:33], v[34:35], v[38:39] op_sel_hi:[1,0]
	v_exp_f32_e32 v40, v40
	v_exp_f32_e32 v32, v32
	v_exp_f32_e32 v33, v33
	v_exp_f32_e32 v41, v41
	global_store_dwordx4 v[36:37], v[44:47], off
	v_add_u32_e32 v37, 0xa0, v148
	v_pk_add_f32 v[32:33], v[32:33], 1.0 op_sel_hi:[1,0]
	v_pk_add_f32 v[40:41], v[40:41], 1.0 op_sel_hi:[1,0]
	v_rcp_f32_e32 v32, v32
	v_rcp_f32_e32 v33, v33
	v_mul_f32_e32 v36, v39, v39
	v_rcp_f32_e32 v40, v40
	v_rcp_f32_e32 v41, v41
	v_pk_mul_f32 v[34:35], v[24:25], v[38:39] op_sel_hi:[1,0]
	v_pk_mul_f32 v[30:31], v[30:31], v[36:37] op_sel_hi:[1,0]
	v_exp_f32_e32 v34, v34
	v_exp_f32_e32 v35, v35
	v_pk_mul_f32 v[30:31], v[30:31], v[32:33]
	v_pk_mul_f32 v[32:33], v[26:27], v[38:39] op_sel_hi:[1,0]
	v_pk_mul_f32 v[28:29], v[28:29], v[36:37] op_sel_hi:[1,0]
	v_exp_f32_e32 v32, v32
	v_exp_f32_e32 v33, v33
	v_pk_mul_f32 v[28:29], v[28:29], v[40:41]
	v_pk_mul_f32 v[20:21], v[20:21], v[36:37] op_sel_hi:[1,0]
	v_cvt_pk_bf16_f32 v28, v28, v29
	v_cvt_pk_bf16_f32 v29, v30, v31
	v_pk_add_f32 v[30:31], v[34:35], 1.0 op_sel_hi:[1,0]
	v_pk_add_f32 v[24:25], v[32:33], 1.0 op_sel_hi:[1,0]
	v_rcp_f32_e32 v30, v30
	v_rcp_f32_e32 v31, v31
	v_rcp_f32_e32 v24, v24
	v_rcp_f32_e32 v25, v25
	v_pk_mul_f32 v[22:23], v[26:27], v[22:23]
	v_pk_mul_f32 v[20:21], v[20:21], v[30:31]
	v_pk_mul_f32 v[12:13], v[16:17], v[12:13]
	v_cvt_pk_bf16_f32 v30, v20, v21
	v_pk_mul_f32 v[20:21], v[22:23], v[36:37] op_sel_hi:[1,0]
	v_pk_mul_f32 v[14:15], v[18:19], v[14:15]
	v_pk_mul_f32 v[20:21], v[20:21], v[24:25]
	v_pk_mul_f32 v[4:5], v[8:9], v[4:5]
	v_cvt_pk_bf16_f32 v31, v20, v21
	v_mov_b32_e32 v26, v166
	v_mad_i64_i32 v[20:21], s[34:35], v37, s31, v[116:117]
	v_lshl_add_u64 v[20:21], v[20:21], 0, v[118:119]
	global_store_dwordx4 v[20:21], v[28:31], off
	v_add_u32_e32 v21, 0xb0, v148
	s_waitcnt lgkmcnt(0)
	v_mul_f32_e32 v20, 0xbfb8aa3b, v26
	v_pk_mul_f32 v[22:23], v[16:17], v[20:21] op_sel_hi:[1,0]
	v_pk_mul_f32 v[16:17], v[18:19], v[20:21] op_sel_hi:[1,0]
	v_exp_f32_e32 v22, v22
	v_exp_f32_e32 v16, v16
	v_exp_f32_e32 v17, v17
	v_exp_f32_e32 v23, v23
	v_mul_f32_e32 v26, v26, v26
	v_pk_mul_f32 v[18:19], v[8:9], v[20:21] op_sel_hi:[1,0]
	v_pk_add_f32 v[16:17], v[16:17], 1.0 op_sel_hi:[1,0]
	v_pk_add_f32 v[22:23], v[22:23], 1.0 op_sel_hi:[1,0]
	v_rcp_f32_e32 v16, v16
	v_rcp_f32_e32 v17, v17
	v_rcp_f32_e32 v22, v22
	v_rcp_f32_e32 v23, v23
	v_exp_f32_e32 v18, v18
	v_exp_f32_e32 v19, v19
	v_pk_mul_f32 v[14:15], v[14:15], v[26:27] op_sel_hi:[1,0]
	v_pk_mul_f32 v[12:13], v[12:13], v[26:27] op_sel_hi:[1,0]
	v_pk_mul_f32 v[14:15], v[14:15], v[16:17]
	v_pk_mul_f32 v[16:17], v[10:11], v[20:21] op_sel_hi:[1,0]
	v_pk_mul_f32 v[12:13], v[12:13], v[22:23]
	v_exp_f32_e32 v16, v16
	v_exp_f32_e32 v17, v17
	v_cvt_pk_bf16_f32 v12, v12, v13
	v_cvt_pk_bf16_f32 v13, v14, v15
	v_pk_add_f32 v[14:15], v[18:19], 1.0 op_sel_hi:[1,0]
	v_pk_add_f32 v[8:9], v[16:17], 1.0 op_sel_hi:[1,0]
	v_rcp_f32_e32 v14, v14
	v_rcp_f32_e32 v15, v15
	v_rcp_f32_e32 v8, v8
	v_rcp_f32_e32 v9, v9
	v_pk_mul_f32 v[4:5], v[4:5], v[26:27] op_sel_hi:[1,0]
	v_mad_i64_i32 v[24:25], s[34:35], v21, s31, v[116:117]
	v_pk_mul_f32 v[6:7], v[10:11], v[6:7]
	v_pk_mul_f32 v[4:5], v[4:5], v[14:15]
	v_lshl_add_u64 v[24:25], v[24:25], 0, v[118:119]
	v_cvt_pk_bf16_f32 v14, v4, v5
	v_pk_mul_f32 v[4:5], v[6:7], v[26:27] op_sel_hi:[1,0]
	s_andn2_b64 vcc, exec, s[38:39]
	s_mov_b64 s[34:35], -1
	v_pk_mul_f32 v[4:5], v[4:5], v[8:9]
	s_nop 0
	v_cvt_pk_bf16_f32 v15, v4, v5
	global_store_dwordx4 v[24:25], v[12:15], off
	s_cbranch_vccnz .LBB0_142
	s_andn2_b64 vcc, exec, s[0:1]
	s_cbranch_vccnz .LBB0_141
	s_barrier
	s_branch .LBB0_141
